# combined: ret_out + conv + SWA cross-item pipelines, counted item-top waits, fused softmax exponent
# baseline (speedup 1.0000x reference)
.Lswp_vhi1:
.Lswp_done:
	v_max3_f32 v0, v19, v28, v24
	v_max3_f32 v0, v0, v26, v25
	v_max3_f32 v0, v0, v29, v27
	v_max3_f32 v0, v0, v31, v30
	v_max3_f32 v0, v0, v33, v32
	v_max3_f32 v0, v0, v35, v34
	v_max3_f32 v0, v0, v38, v36
	v_max3_f32 v0, v0, v40, v39
	v_max3_f32 v0, v0, v43, v41
	v_max3_f32 v0, v0, v45, v44
	v_max3_f32 v0, v0, v47, v46
	v_max3_f32 v0, v0, v49, v48
	v_max3_f32 v0, v0, v51, v50
	v_max3_f32 v0, v0, v53, v52
	v_max3_f32 v0, v0, v59, v58
	v_max3_f32 v0, v0, v66, v67
	v_max3_f32 v0, v0, v95, v94
	v_max3_f32 v0, v0, v97, v96
	v_max3_f32 v0, v0, v99, v98
	v_max3_f32 v0, v0, v101, v100
	v_max3_f32 v0, v0, v103, v102
	v_max3_f32 v0, v0, v105, v104
	v_max3_f32 v0, v0, v107, v106
	v_max3_f32 v0, v0, v109, v108
	v_max3_f32 v0, v0, v111, v110
	v_max3_f32 v0, v0, v113, v112
	v_max3_f32 v0, v0, v115, v114
	v_max3_f32 v0, v0, v117, v116
	v_max3_f32 v0, v0, v119, v118
	v_max3_f32 v0, v0, v121, v120
	v_max3_f32 v0, v0, v123, v122
	v_max3_f32 v0, v0, v125, v124
	v_max3_f32 v0, v0, v127, v126
	v_add_u32_e32 v1, 64, v242
	v_max3_f32 v0, v0, v129, v128
	v_cmp_lt_i32_e32 vcc, v237, v1
	v_max3_f32 v0, v0, v6, v7
	v_max3_f32 v0, v0, v131, v130
	v_cndmask_b32_e32 v2, v220, v237, vcc
	v_lshlrev_b32_e32 v132, 2, v2
	ds_bpermute_b32 v2, v132, v0
	v_cmp_lt_i32_e32 vcc, v236, v1
	s_lshl_b32 s0, s25, 6
	s_lshl_b32 s0, s0, 1
	s_waitcnt lgkmcnt(0)
	v_max_f32_e32 v2, v2, v2
	v_cndmask_b32_e32 v1, v220, v236, vcc
	v_max_f32_e32 v0, v0, v2
	v_lshlrev_b32_e32 v134, 2, v1
	ds_bpermute_b32 v1, v134, v0
	s_xor_b64 s[18:19], s[20:21], -1
	s_mov_b32 s97, 1
	s_mov_b64 s[20:21], 0
	s_and_b64 vcc, exec, s[18:19]
	s_waitcnt lgkmcnt(0)
	v_max_f32_e32 v1, v1, v1
	v_max_f32_e32 v133, v0, v1
	v_mul_f32_e32 v147, 0xbfb8aa3b, v133
	v_fmamk_f32 v1, v24, 0x3fb8aa3b, v147
	v_exp_f32_e32 v71, v1
	v_fmamk_f32 v1, v26, 0x3fb8aa3b, v147
	v_exp_f32_e32 v78, v1
	v_fmamk_f32 v1, v25, 0x3fb8aa3b, v147
	v_exp_f32_e32 v79, v1
	v_fmamk_f32 v1, v29, 0x3fb8aa3b, v147
	v_exp_f32_e32 v82, v1
	v_fmamk_f32 v1, v27, 0x3fb8aa3b, v147
	v_exp_f32_e32 v83, v1
	v_fmamk_f32 v1, v31, 0x3fb8aa3b, v147
	v_exp_f32_e32 v84, v1
	v_fmamk_f32 v1, v30, 0x3fb8aa3b, v147
	v_exp_f32_e32 v85, v1
	v_fmamk_f32 v1, v33, 0x3fb8aa3b, v147
	v_exp_f32_e32 v64, v1
	v_fmamk_f32 v1, v32, 0x3fb8aa3b, v147
	v_exp_f32_e32 v65, v1
	v_fmamk_f32 v1, v35, 0x3fb8aa3b, v147
	v_exp_f32_e32 v72, v1
	v_fmamk_f32 v1, v34, 0x3fb8aa3b, v147
	v_exp_f32_e32 v73, v1
	v_fmamk_f32 v1, v38, 0x3fb8aa3b, v147
	v_exp_f32_e32 v76, v1
	v_fmamk_f32 v1, v36, 0x3fb8aa3b, v147
	v_exp_f32_e32 v77, v1
	v_fmamk_f32 v1, v40, 0x3fb8aa3b, v147
	v_exp_f32_e32 v80, v1
	v_fmamk_f32 v1, v39, 0x3fb8aa3b, v147
	v_exp_f32_e32 v81, v1
	v_fmamk_f32 v1, v43, 0x3fb8aa3b, v147
	v_exp_f32_e32 v56, v1
	v_fmamk_f32 v1, v41, 0x3fb8aa3b, v147
	v_exp_f32_e32 v57, v1
	v_fmamk_f32 v1, v45, 0x3fb8aa3b, v147
	v_exp_f32_e32 v62, v1
	v_fmamk_f32 v1, v44, 0x3fb8aa3b, v147
	v_exp_f32_e32 v63, v1
	v_fmamk_f32 v1, v47, 0x3fb8aa3b, v147
	v_exp_f32_e32 v68, v1
	v_fmamk_f32 v1, v46, 0x3fb8aa3b, v147
	v_exp_f32_e32 v69, v1
	v_fmamk_f32 v1, v49, 0x3fb8aa3b, v147
	v_exp_f32_e32 v74, v1
	v_fmamk_f32 v1, v48, 0x3fb8aa3b, v147
	v_exp_f32_e32 v75, v1
	v_fmamk_f32 v1, v51, 0x3fb8aa3b, v147
	v_exp_f32_e32 v48, v1
	v_fmamk_f32 v1, v50, 0x3fb8aa3b, v147
	v_exp_f32_e32 v49, v1
	v_fmamk_f32 v1, v53, 0x3fb8aa3b, v147
	v_exp_f32_e32 v54, v1
	v_fmamk_f32 v1, v52, 0x3fb8aa3b, v147
	v_exp_f32_e32 v55, v1
	v_fmamk_f32 v1, v59, 0x3fb8aa3b, v147
	v_exp_f32_e32 v60, v1
	v_fmamk_f32 v1, v58, 0x3fb8aa3b, v147
	v_exp_f32_e32 v61, v1
	v_fmamk_f32 v1, v66, 0x3fb8aa3b, v147
	v_exp_f32_e32 v66, v1
	v_fmamk_f32 v1, v67, 0x3fb8aa3b, v147
	v_fmamk_f32 v0, v28, 0x3fb8aa3b, v147
	v_exp_f32_e32 v67, v1
	v_fmamk_f32 v1, v95, 0x3fb8aa3b, v147
	v_exp_f32_e32 v70, v0
	v_exp_f32_e32 v40, v1
	v_fmamk_f32 v1, v94, 0x3fb8aa3b, v147
	v_exp_f32_e32 v41, v1
	v_fmamk_f32 v1, v97, 0x3fb8aa3b, v147
	v_add_f32_e32 v0, 0, v70
	v_add_f32_e32 v0, v71, v0
	v_exp_f32_e32 v46, v1
	v_fmamk_f32 v1, v96, 0x3fb8aa3b, v147
	v_add_f32_e32 v0, v78, v0
	v_add_f32_e32 v0, v79, v0
	v_exp_f32_e32 v47, v1
	v_fmamk_f32 v1, v99, 0x3fb8aa3b, v147
	v_add_f32_e32 v0, v82, v0
	v_add_f32_e32 v0, v83, v0
	v_exp_f32_e32 v52, v1
	v_fmamk_f32 v1, v98, 0x3fb8aa3b, v147
	v_add_f32_e32 v0, v84, v0
	v_add_f32_e32 v0, v85, v0
	v_exp_f32_e32 v53, v1
	v_fmamk_f32 v1, v101, 0x3fb8aa3b, v147
	v_add_f32_e32 v0, v64, v0
	v_add_f32_e32 v0, v65, v0
	v_exp_f32_e32 v58, v1
	v_fmamk_f32 v1, v100, 0x3fb8aa3b, v147
	v_add_f32_e32 v0, v72, v0
	v_add_f32_e32 v0, v73, v0
	v_exp_f32_e32 v59, v1
	v_fmamk_f32 v1, v103, 0x3fb8aa3b, v147
	v_add_f32_e32 v0, v76, v0
	v_add_f32_e32 v0, v77, v0
	v_exp_f32_e32 v30, v1
	v_fmamk_f32 v1, v102, 0x3fb8aa3b, v147
	v_add_f32_e32 v0, v80, v0
	v_add_f32_e32 v0, v81, v0
	v_exp_f32_e32 v31, v1
	v_fmamk_f32 v1, v105, 0x3fb8aa3b, v147
	v_add_f32_e32 v0, v56, v0
	v_add_f32_e32 v0, v57, v0
	v_exp_f32_e32 v38, v1
	v_fmamk_f32 v1, v104, 0x3fb8aa3b, v147
	v_add_f32_e32 v0, v62, v0
	v_add_f32_e32 v0, v63, v0
	v_exp_f32_e32 v39, v1
	v_fmamk_f32 v1, v107, 0x3fb8aa3b, v147
	v_add_f32_e32 v0, v68, v0
	v_add_f32_e32 v0, v69, v0
	v_exp_f32_e32 v44, v1
	v_fmamk_f32 v1, v106, 0x3fb8aa3b, v147
	v_add_f32_e32 v0, v74, v0
	v_add_f32_e32 v0, v75, v0
	v_exp_f32_e32 v45, v1
	v_fmamk_f32 v1, v109, 0x3fb8aa3b, v147
	v_add_f32_e32 v0, v48, v0
	v_add_f32_e32 v0, v49, v0
	v_exp_f32_e32 v50, v1
	v_fmamk_f32 v1, v108, 0x3fb8aa3b, v147
	v_add_f32_e32 v0, v54, v0
	v_add_f32_e32 v0, v55, v0
	v_exp_f32_e32 v51, v1
	v_fmamk_f32 v1, v111, 0x3fb8aa3b, v147
	v_add_f32_e32 v0, v60, v0
	v_add_f32_e32 v0, v61, v0
	v_exp_f32_e32 v10, v1
	v_fmamk_f32 v1, v110, 0x3fb8aa3b, v147
	v_add_f32_e32 v0, v66, v0
	v_add_f32_e32 v0, v67, v0
	v_exp_f32_e32 v11, v1
	v_fmamk_f32 v1, v113, 0x3fb8aa3b, v147
	v_add_f32_e32 v0, v40, v0
	v_add_f32_e32 v0, v41, v0
	v_exp_f32_e32 v28, v1
	v_fmamk_f32 v1, v112, 0x3fb8aa3b, v147
	v_add_f32_e32 v0, v46, v0
	v_add_f32_e32 v0, v47, v0
	v_exp_f32_e32 v29, v1
	v_fmamk_f32 v1, v115, 0x3fb8aa3b, v147
	v_add_f32_e32 v0, v52, v0
	v_add_f32_e32 v0, v53, v0
	v_exp_f32_e32 v34, v1
	v_fmamk_f32 v1, v114, 0x3fb8aa3b, v147
	v_add_f32_e32 v0, v58, v0
	v_add_f32_e32 v0, v59, v0
	v_exp_f32_e32 v35, v1
	v_fmamk_f32 v1, v117, 0x3fb8aa3b, v147
	v_add_f32_e32 v0, v30, v0
	v_add_f32_e32 v0, v31, v0
	v_exp_f32_e32 v42, v1
	v_fmamk_f32 v1, v116, 0x3fb8aa3b, v147
	v_add_f32_e32 v0, v38, v0
	v_add_f32_e32 v0, v39, v0
	v_exp_f32_e32 v43, v1
	v_fmamk_f32 v1, v119, 0x3fb8aa3b, v147
	v_add_f32_e32 v0, v44, v0
	v_add_f32_e32 v0, v45, v0
	v_exp_f32_e32 v4, v1
	v_fmamk_f32 v1, v118, 0x3fb8aa3b, v147
	v_add_f32_e32 v0, v50, v0
	v_add_f32_e32 v0, v51, v0
	v_exp_f32_e32 v5, v1
	v_fmamk_f32 v1, v121, 0x3fb8aa3b, v147
	v_add_f32_e32 v0, v10, v0
	v_add_f32_e32 v0, v11, v0
	v_exp_f32_e32 v8, v1
	v_fmamk_f32 v1, v120, 0x3fb8aa3b, v147
	v_add_f32_e32 v0, v28, v0
	v_add_f32_e32 v0, v29, v0
	v_exp_f32_e32 v9, v1
	v_fmamk_f32 v1, v123, 0x3fb8aa3b, v147
	v_add_f32_e32 v0, v34, v0
	v_add_f32_e32 v0, v35, v0
	v_exp_f32_e32 v26, v1
	v_fmamk_f32 v1, v122, 0x3fb8aa3b, v147
	v_add_f32_e32 v0, v42, v0
	v_add_f32_e32 v0, v43, v0
	v_exp_f32_e32 v27, v1
	v_fmamk_f32 v1, v125, 0x3fb8aa3b, v147
	v_add_f32_e32 v0, v4, v0
	v_add_f32_e32 v0, v5, v0
	v_exp_f32_e32 v32, v1
	v_fmamk_f32 v1, v124, 0x3fb8aa3b, v147
	v_add_f32_e32 v0, v8, v0
	v_add_f32_e32 v0, v9, v0
	v_exp_f32_e32 v33, v1
	v_add_f32_e32 v0, v26, v0
	v_add_f32_e32 v0, v27, v0
	v_add_f32_e32 v0, v32, v0
	v_add_f32_e32 v1, v33, v0
	v_fmamk_f32 v0, v127, 0x3fb8aa3b, v147
	v_exp_f32_e32 v0, v0
	v_sub_f32_e32 v6, v6, v133
	v_mul_f32_e32 v6, 0x3fb8aa3b, v6
	v_sub_f32_e32 v7, v7, v133
	v_add_f32_e32 v2, v0, v1
	v_fmamk_f32 v1, v126, 0x3fb8aa3b, v147
	v_exp_f32_e32 v1, v1
	v_exp_f32_e32 v6, v6
	v_mul_f32_e32 v7, 0x3fb8aa3b, v7
	v_exp_f32_e32 v7, v7
	v_add_f32_e32 v3, v1, v2
	v_fmamk_f32 v2, v129, 0x3fb8aa3b, v147
	v_exp_f32_e32 v2, v2
	v_sub_f32_e32 v19, v19, v133
	v_mul_f32_e32 v19, 0x3fb8aa3b, v19
	v_exp_f32_e32 v19, v19
	v_add_f32_e32 v24, v2, v3
	v_fmamk_f32 v3, v128, 0x3fb8aa3b, v147
	v_exp_f32_e32 v3, v3
	ds_read_b128 v[98:101], v15 offset:64768
	ds_read_b128 v[102:105], v86 offset:25088
	ds_read_b128 v[106:109], v86 offset:37632
	v_add_f32_e32 v24, v3, v24
	v_add_f32_e32 v24, v6, v24
	v_add_f32_e32 v25, v7, v24
	v_fmamk_f32 v24, v131, 0x3fb8aa3b, v147
	v_exp_f32_e32 v24, v24
	s_nop 0
	v_add_f32_e32 v36, v24, v25
	v_fmamk_f32 v25, v130, 0x3fb8aa3b, v147
	v_exp_f32_e32 v25, v25
	s_nop 0
	v_add_f32_e32 v36, v25, v36
	ds_bpermute_b32 v94, v132, v36
	s_waitcnt lgkmcnt(0)
	v_add_f32_e32 v36, v36, v94
	ds_bpermute_b32 v94, v134, v36
	s_waitcnt lgkmcnt(0)
	v_add_f32_e32 v36, v36, v94
	v_add_f32_e32 v19, v19, v36
	v_rcp_f32_e32 v36, v19
	s_nop 0
	v_pk_mul_f32 v[70:71], v[70:71], v[36:37] op_sel_hi:[1,0]
	v_pk_mul_f32 v[78:79], v[78:79], v[36:37] op_sel_hi:[1,0]
	v_cvt_pk_bf16_f32 v94, v70, v71
	v_cvt_pk_bf16_f32 v95, v78, v79
	v_pk_mul_f32 v[70:71], v[82:83], v[36:37] op_sel_hi:[1,0]
	v_pk_mul_f32 v[78:79], v[84:85], v[36:37] op_sel_hi:[1,0]
	ds_read_b128 v[82:85], v15 offset:52224
	v_pk_mul_f32 v[64:65], v[64:65], v[36:37] op_sel_hi:[1,0]
	v_cvt_pk_bf16_f32 v96, v70, v71
	v_pk_mul_f32 v[72:73], v[72:73], v[36:37] op_sel_hi:[1,0]
	v_cvt_pk_bf16_f32 v70, v64, v65
	v_pk_mul_f32 v[64:65], v[76:77], v[36:37] op_sel_hi:[1,0]
	v_pk_mul_f32 v[76:77], v[80:81], v[36:37] op_sel_hi:[1,0]
	v_cvt_pk_bf16_f32 v97, v78, v79
	v_cvt_pk_bf16_f32 v71, v72, v73
	v_cvt_pk_bf16_f32 v73, v76, v77
	ds_read_b128 v[76:79], v15 offset:52288
	s_waitcnt lgkmcnt(1)
	v_mfma_f32_16x16x32_bf16 v[82:85], v[82:85], v[94:97], 0
	v_cvt_pk_bf16_f32 v72, v64, v65
	v_pk_mul_f32 v[56:57], v[56:57], v[36:37] op_sel_hi:[1,0]
	v_pk_mul_f32 v[64:65], v[62:63], v[36:37] op_sel_hi:[1,0]
	s_waitcnt lgkmcnt(0)
	v_mfma_f32_16x16x32_bf16 v[76:79], v[76:79], v[70:73], v[82:85]
	s_nop 2
	ds_read_b128 v[80:83], v15 offset:64832
	v_cvt_pk_bf16_f32 v62, v56, v57
	v_pk_mul_f32 v[56:57], v[68:69], v[36:37] op_sel_hi:[1,0]
	v_mfma_f32_16x16x32_bf16 v[98:101], v[98:101], v[94:97], 0
	v_mul_f32_e64 v68, v74, v36
	v_mul_f32_e64 v69, v75, v36
	v_cvt_pk_bf16_f32 v63, v64, v65
	v_cvt_pk_bf16_f32 v64, v56, v57
	s_waitcnt lgkmcnt(0)
	v_mfma_f32_16x16x32_bf16 v[80:83], v[80:83], v[70:73], v[98:101]
	v_cvt_pk_bf16_f32 v65, v68, v69
	s_nop 1
	ds_read_b128 v[98:101], v86 offset:25152
	v_pk_mul_f32 v[48:49], v[48:49], v[36:37] op_sel_hi:[1,0]
	v_mfma_f32_16x16x32_bf16 v[102:105], v[102:105], v[94:97], 0
	v_mul_f32_e64 v56, v54, v36
	v_mul_f32_e64 v57, v55, v36
	v_cvt_pk_bf16_f32 v54, v48, v49
	v_pk_mul_f32 v[48:49], v[60:61], v[36:37] op_sel_hi:[1,0]
	s_waitcnt lgkmcnt(0)
	v_mfma_f32_16x16x32_bf16 v[98:101], v[98:101], v[70:73], v[102:105]
	v_mul_f32_e64 v60, v66, v36
	v_mul_f32_e64 v61, v67, v36
	s_nop 0
	ds_read_b128 v[102:105], v86 offset:37696
	v_mfma_f32_16x16x32_bf16 v[94:97], v[106:109], v[94:97], 0
	v_cvt_pk_bf16_f32 v55, v56, v57
	v_cvt_pk_bf16_f32 v56, v48, v49
	v_cvt_pk_bf16_f32 v57, v60, v61
	s_waitcnt lgkmcnt(0)
	v_mfma_f32_16x16x32_bf16 v[70:73], v[102:105], v[70:73], v[94:97]
	v_mul_f32_e64 v40, v40, v36
	v_mul_f32_e64 v41, v41, v36
	s_nop 0
	ds_read_b128 v[94:97], v15 offset:52352
	v_pk_mul_f32 v[48:49], v[46:47], v[36:37] op_sel_hi:[1,0]
	s_waitcnt lgkmcnt(0)
	v_mfma_f32_16x16x32_bf16 v[74:77], v[94:97], v[62:65], v[76:79]
	ds_read_b128 v[94:97], v15 offset:64896
	v_cvt_pk_bf16_f32 v46, v40, v41
	v_pk_mul_f32 v[40:41], v[52:53], v[36:37] op_sel_hi:[1,0]
	s_waitcnt lgkmcnt(0)
	v_mfma_f32_16x16x32_bf16 v[78:81], v[94:97], v[62:65], v[80:83]
	s_nop 2
	ds_read_b128 v[82:85], v86 offset:25216
	ds_read_b128 v[94:97], v86 offset:37760
	s_waitcnt lgkmcnt(1)
	v_mfma_f32_16x16x32_bf16 v[82:85], v[82:85], v[62:65], v[98:101]
	ds_read_b128 v[66:69], v15 offset:52416
	v_pk_mul_f32 v[52:53], v[58:59], v[36:37] op_sel_hi:[1,0]
	v_cvt_pk_bf16_f32 v47, v48, v49
	s_waitcnt lgkmcnt(1)
	v_mfma_f32_16x16x32_bf16 v[62:65], v[94:97], v[62:65], v[70:73]
	v_cvt_pk_bf16_f32 v48, v40, v41
	v_cvt_pk_bf16_f32 v49, v52, v53
	v_pk_mul_f32 v[30:31], v[30:31], v[36:37] op_sel_hi:[1,0]
	ds_read_b128 v[70:73], v15 offset:64960
	s_waitcnt lgkmcnt(1)
	v_mfma_f32_16x16x32_bf16 v[66:69], v[66:69], v[54:57], v[74:77]
	v_mul_f32_e64 v40, v38, v36
	v_mul_f32_e64 v41, v39, v36
	v_cvt_pk_bf16_f32 v38, v30, v31
	ds_read_b128 v[74:77], v86 offset:25280
	s_waitcnt lgkmcnt(1)
	v_mfma_f32_16x16x32_bf16 v[70:73], v[70:73], v[54:57], v[78:81]
	s_nop 2
	ds_read_b128 v[78:81], v86 offset:37824
	ds_read_b128 v[58:61], v15 offset:52480
	s_waitcnt lgkmcnt(2)
	v_mfma_f32_16x16x32_bf16 v[74:77], v[74:77], v[54:57], v[82:85]
	v_mul_f32_e64 v30, v44, v36
	v_mul_f32_e64 v31, v45, v36
	v_pk_mul_f32 v[44:45], v[50:51], v[36:37] op_sel_hi:[1,0]
	v_cvt_pk_bf16_f32 v39, v40, v41
	s_waitcnt lgkmcnt(1)
	v_mfma_f32_16x16x32_bf16 v[54:57], v[78:81], v[54:57], v[62:65]
	v_cvt_pk_bf16_f32 v40, v30, v31
	v_cvt_pk_bf16_f32 v41, v44, v45
	s_nop 0
	ds_read_b128 v[62:65], v15 offset:65024
	s_waitcnt lgkmcnt(1)
	v_mfma_f32_16x16x32_bf16 v[58:61], v[58:61], v[46:49], v[66:69]
	v_mul_f32_e64 v10, v10, v36
	v_mul_f32_e64 v11, v11, v36
	v_pk_mul_f32 v[30:31], v[28:29], v[36:37] op_sel_hi:[1,0]
	v_cvt_pk_bf16_f32 v28, v10, v11
	s_waitcnt lgkmcnt(0)
	v_mfma_f32_16x16x32_bf16 v[62:65], v[62:65], v[46:49], v[70:73]
	ds_read_b128 v[66:69], v86 offset:25344
	s_nop 1
	ds_read_b128 v[70:73], v86 offset:37888
	s_waitcnt lgkmcnt(1)
	v_mfma_f32_16x16x32_bf16 v[66:69], v[66:69], v[46:49], v[74:77]
	ds_read_b128 v[50:53], v15 offset:52544
	v_pk_mul_f32 v[10:11], v[34:35], v[36:37] op_sel_hi:[1,0]
	v_pk_mul_f32 v[34:35], v[42:43], v[36:37] op_sel_hi:[1,0]
	s_waitcnt lgkmcnt(1)
	v_mfma_f32_16x16x32_bf16 v[46:49], v[70:73], v[46:49], v[54:57]
	v_cvt_pk_bf16_f32 v29, v30, v31
	v_cvt_pk_bf16_f32 v30, v10, v11
	v_cvt_pk_bf16_f32 v31, v34, v35
	ds_read_b128 v[54:57], v15 offset:65088
	s_waitcnt lgkmcnt(1)
	v_mfma_f32_16x16x32_bf16 v[50:53], v[50:53], v[38:41], v[58:61]
	v_mul_f32_e64 v4, v4, v36
	v_mul_f32_e64 v5, v5, v36
	v_pk_mul_f32 v[10:11], v[8:9], v[36:37] op_sel_hi:[1,0]
	ds_read_b128 v[58:61], v86 offset:25408
	s_waitcnt lgkmcnt(1)
	v_mfma_f32_16x16x32_bf16 v[54:57], v[54:57], v[38:41], v[62:65]
	s_nop 2
	ds_read_b128 v[62:65], v86 offset:37952
	ds_read_b128 v[42:45], v15 offset:52608
	s_waitcnt lgkmcnt(2)
	v_mfma_f32_16x16x32_bf16 v[58:61], v[58:61], v[38:41], v[66:69]
	v_cvt_pk_bf16_f32 v8, v4, v5
	v_pk_mul_f32 v[4:5], v[26:27], v[36:37] op_sel_hi:[1,0]
	v_pk_mul_f32 v[26:27], v[32:33], v[36:37] op_sel_hi:[1,0]
	s_waitcnt lgkmcnt(1)
	v_mfma_f32_16x16x32_bf16 v[38:41], v[62:65], v[38:41], v[46:49]
	v_cvt_pk_bf16_f32 v9, v10, v11
	v_cvt_pk_bf16_f32 v10, v4, v5
	s_nop 0
	ds_read_b128 v[46:49], v15 offset:65152
	s_waitcnt lgkmcnt(1)
	v_mfma_f32_16x16x32_bf16 v[42:45], v[42:45], v[28:31], v[50:53]
	v_cvt_pk_bf16_f32 v11, v26, v27
	v_pk_mul_f32 v[0:1], v[0:1], v[36:37] op_sel_hi:[1,0]
	v_pk_mul_f32 v[2:3], v[2:3], v[36:37] op_sel_hi:[1,0]
	s_waitcnt lgkmcnt(0)
	v_mfma_f32_16x16x32_bf16 v[46:49], v[46:49], v[28:31], v[54:57]
	ds_read_b128 v[50:53], v86 offset:25472
	s_nop 1
	ds_read_b128 v[54:57], v86 offset:38016
	s_waitcnt lgkmcnt(1)
	v_mfma_f32_16x16x32_bf16 v[50:53], v[50:53], v[28:31], v[58:61]
	ds_read_b128 v[32:35], v15 offset:52672
	v_cvt_pk_bf16_f32 v0, v0, v1
	v_cvt_pk_bf16_f32 v1, v2, v3
	s_waitcnt lgkmcnt(1)
	v_mfma_f32_16x16x32_bf16 v[28:31], v[54:57], v[28:31], v[38:41]
	v_mul_f32_e64 v2, v6, v36
	v_mul_f32_e64 v3, v7, v36
	v_pk_mul_f32 v[4:5], v[24:25], v[36:37] op_sel_hi:[1,0]
	v_cvt_pk_bf16_f32 v2, v2, v3
	ds_read_b128 v[38:41], v15 offset:65216
	s_waitcnt lgkmcnt(1)
	v_mfma_f32_16x16x32_bf16 v[32:35], v[32:35], v[8:11], v[42:45]
	v_cvt_pk_bf16_f32 v3, v4, v5
	s_nop 1
	ds_read_b128 v[42:45], v86 offset:25536
	s_waitcnt lgkmcnt(1)
	v_mfma_f32_16x16x32_bf16 v[38:41], v[38:41], v[8:11], v[46:49]
	s_nop 2
	ds_read_b128 v[46:49], v86 offset:38080
	ds_read_b128 v[4:7], v15 offset:52736
	ds_read_b128 v[24:27], v15 offset:65280
	s_waitcnt lgkmcnt(3)
	v_mfma_f32_16x16x32_bf16 v[42:45], v[42:45], v[8:11], v[50:53]
	s_waitcnt lgkmcnt(2)
	v_mfma_f32_16x16x32_bf16 v[8:11], v[46:49], v[8:11], v[28:31]
	s_nop 2
	ds_read_b128 v[28:31], v86 offset:25600
	s_waitcnt lgkmcnt(2)
	v_mfma_f32_16x16x32_bf16 v[4:7], v[4:7], v[0:3], v[32:35]
	s_nop 2
	ds_read_b128 v[32:35], v86 offset:38144
	s_waitcnt lgkmcnt(2)
	v_mfma_f32_16x16x32_bf16 v[24:27], v[24:27], v[0:3], v[38:41]
	s_nop 1
	v_cvt_pk_bf16_f32 v4, v4, v5
	v_cvt_pk_bf16_f32 v5, v6, v7
	s_waitcnt lgkmcnt(1)
	v_mfma_f32_16x16x32_bf16 v[28:31], v[28:31], v[0:3], v[42:45]
	s_waitcnt lgkmcnt(0)
	v_mfma_f32_16x16x32_bf16 v[0:3], v[32:35], v[0:3], v[8:11]
	v_cvt_pk_bf16_f32 v6, v24, v25
	v_cvt_pk_bf16_f32 v7, v26, v27
	s_nop 0
	v_lshl_add_u64 v[8:9], v[22:23], 0, s[0:1]
	global_store_dwordx4 v[8:9], v[4:7], off
	s_nop 1
	v_cvt_pk_bf16_f32 v4, v28, v29
	v_cvt_pk_bf16_f32 v5, v30, v31
	v_cvt_pk_bf16_f32 v6, v0, v1
	v_cvt_pk_bf16_f32 v7, v2, v3
	global_store_dwordx4 v[8:9], v[4:7], off offset:64
	s_cbranch_vccnz .LBB0_679
